# P2 queue split into 8 per-XCD queues; XCD x processes every mixer unit of batch element x (L2 locality for K/V re-reads)
# speedup vs baseline: 1.0229x; 1.0040x over previous
; __global__ void __launch_bounds__(512) hybrid_fwd(Params p) {
;     ...
;             unsigned* ctl = (unsigned*)(C.ws + WS_CTL);
;             __syncthreads();
;             if (C.tid == 0) s_unit = (int)atomicAdd(ctl + 64 * (1 + l), 1u);
;             __syncthreads();
.LBB0_317:
	s_mov_b64 s[20:21], 0
	v_mov_b32_e32 v132, v229
	s_add_u32 s64, s92, s20
	s_addc_u32 s65, s93, s21
	v_readfirstlane_b32 s73, v132
	v_cmp_eq_u32_e64 s[38:39], 0, v132
	s_barrier
	s_and_saveexec_b64 s[40:41], s[38:39]
	s_cbranch_execz .LBB0_321
	s_mov_b64 s[44:45], exec
	v_mbcnt_lo_u32_b32 v0, s44, 0
	v_mbcnt_hi_u32_b32 v0, s45, v0
	v_cmp_eq_u32_e32 vcc, 0, v0
	s_and_saveexec_b64 s[42:43], vcc
	s_cbranch_execz .LBB0_320
	s_add_u32 s20, s64, s62
	s_addc_u32 s21, s65, s63
	s_getreg_b32 s22, hwreg(HW_REG_XCC_ID, 0, 4)
	s_and_b32 s22, s22, 7
	s_lshl_b32 s22, s22, 9
	s_add_u32 s20, s20, s22
	s_addc_u32 s21, s21, 0
	s_add_u32 s20, s20, 0x200
	s_addc_u32 s21, s21, 0
	s_bcnt1_i32_b64 s19, s[44:45]
	v_mov_b32_e32 v1, s19
	global_atomic_add v1, v193, v1, s[20:21] offset:256 sc0

; __global__ void __launch_bounds__(512) hybrid_fwd(Params p) {
;     ...
;             if (C.tid == 0) s_unit = (int)atomicAdd(ctl + 64 * (1 + l), 1u);
;             __syncthreads();
;             const int u = s_unit;
;             __syncthreads();
;             if (u >= 1024 + 1024 + 512) break;
;             const int v2 = u - 512, grpq = v2 >> 7, rq = v2 & 127;
;     ...
;             if (u >= 512 && rq < 64) lru_unit(C, p, l, grpq * 64 + rq);
;     ...
;             if (u >= 512 && rq >= 64) moba_unit(C, grpq * 64 + (rq - 64), (const float*)(C.ws + WS_KM) + (size_t)l * 128 * 512);
;     ...
;             if (u < 512) attnA_unit(C, u);
.LBB0_321:
	s_or_b64 exec, exec, s[40:41]
	s_waitcnt lgkmcnt(0)
	s_barrier
	ds_read_b32 v0, v193
	s_movk_i32 s19, 0x13f
	s_mov_b64 s[40:41], -1
	s_waitcnt lgkmcnt(0)
	s_barrier
	v_cmp_lt_i32_e32 vcc, s19, v0
	v_readfirstlane_b32 s74, v0
	s_cbranch_vccnz .LBB0_316
	s_getreg_b32 s22, hwreg(HW_REG_XCC_ID, 0, 4)
	s_and_b32 s22, s22, 7
	s_cmp_lt_u32 s74, 64
	s_cbranch_scc0 .Lq5_b
	s_lshl_b32 s19, s22, 6
	s_add_u32 s74, s74, s19
	s_branch .Lq5_done
.Lq5_b:
	s_sub_u32 s19, s74, 64
	s_lshr_b32 s20, s19, 4
	s_lshl_b32 s20, s20, 7
	s_lshl_b32 s22, s22, 3
	s_add_u32 s20, s20, s22
	s_and_b32 s22, s19, 7
	s_add_u32 s20, s20, s22
	s_bfe_u32 s22, s19, 0x10003
	s_lshl_b32 s22, s22, 6
	s_add_u32 s20, s20, s22
	s_add_u32 s74, s20, 512
